# GEMM K-loops: post-MFMA s_barrier moved up above last 4 MFMAs with s_setprio 2 (early barrier signal)
# speedup vs baseline: 1.0013x; 1.0013x over previous
.LBB0_262:
	s_add_u32 s2, s0, 0xfff80080
	s_addc_u32 s3, s1, -1
	s_add_i32 s6, 0, 0x10000
	s_cmp_eq_u32 s48, 28
	s_cselect_b32 s9, s25, s3
	s_cselect_b32 s8, s33, s2
	s_cselect_b32 s5, s39, s47
	s_cselect_b32 s4, s41, s46
	s_add_i32 s7, 0, 0x14000
	v_add_u32_e32 v174, s6, v10
	v_add_u32_e32 v190, s7, v10
	ds_read_b128 v[146:149], v174
	ds_read_b128 v[166:169], v174 offset:1024
	ds_read_b128 v[170:173], v174 offset:2048
	ds_read_b128 v[174:177], v174 offset:3072
	ds_read_b128 v[178:181], v190
	ds_read_b128 v[182:185], v190 offset:1024
	ds_read_b128 v[186:189], v190 offset:2048
	ds_read_b128 v[190:193], v190 offset:3072
	v_lshl_add_u64 v[212:213], s[0:1], 0, v[142:143]
	s_add_i32 m0, s15, 0xc000
	ds_read_b128 v[194:197], v161
	ds_read_b128 v[198:201], v161 offset:1024
	ds_read_b128 v[202:205], v161 offset:2048
	ds_read_b128 v[228:231], v161 offset:3072
	ds_read_b128 v[232:235], v161 offset:4096
	ds_read_b128 v[236:239], v161 offset:5120
	ds_read_b128 v[240:243], v161 offset:6144
	ds_read_b128 v[244:247], v161 offset:7168
	global_load_lds_dwordx4 v[212:213], off
	v_lshl_add_u64 v[212:213], s[0:1], 0, v[144:145]
	s_add_i32 m0, s15, 0xe000
	s_nop 0
	global_load_lds_dwordx4 v[212:213], off
	s_waitcnt vmcnt(8)
	s_waitcnt lgkmcnt(0)
	s_barrier
	s_setprio 1
	s_waitcnt lgkmcnt(0)
	v_mfma_f32_16x16x32_bf16 v[128:131], v[146:149], v[194:197], v[128:131]
	v_mfma_f32_16x16x32_bf16 v[124:127], v[170:173], v[194:197], v[124:127]
	v_mfma_f32_16x16x32_bf16 v[112:115], v[146:149], v[202:205], v[112:115]
	v_mfma_f32_16x16x32_bf16 v[108:111], v[170:173], v[202:205], v[108:111]
	v_mfma_f32_16x16x32_bf16 v[96:99], v[146:149], v[232:235], v[96:99]
	v_mfma_f32_16x16x32_bf16 v[92:95], v[170:173], v[232:235], v[92:95]
	v_mfma_f32_16x16x32_bf16 v[80:83], v[146:149], v[240:243], v[80:83]
	v_mfma_f32_16x16x32_bf16 v[76:79], v[170:173], v[240:243], v[76:79]
	v_mfma_f32_16x16x32_bf16 v[128:131], v[166:169], v[198:201], v[128:131]
	v_mfma_f32_16x16x32_bf16 v[124:127], v[174:177], v[198:201], v[124:127]
	v_mfma_f32_16x16x32_bf16 v[112:115], v[166:169], v[228:231], v[112:115]
	v_mfma_f32_16x16x32_bf16 v[108:111], v[174:177], v[228:231], v[108:111]
	v_mfma_f32_16x16x32_bf16 v[96:99], v[166:169], v[236:239], v[96:99]
	v_mfma_f32_16x16x32_bf16 v[92:95], v[174:177], v[236:239], v[92:95]
	v_mfma_f32_16x16x32_bf16 v[80:83], v[166:169], v[244:247], v[80:83]
	v_mfma_f32_16x16x32_bf16 v[76:79], v[174:177], v[244:247], v[76:79]
	s_setprio 0
	s_setprio 1
	v_mfma_f32_16x16x32_bf16 v[120:123], v[178:181], v[194:197], v[120:123]
	v_mfma_f32_16x16x32_bf16 v[116:119], v[186:189], v[194:197], v[116:119]
	v_mfma_f32_16x16x32_bf16 v[104:107], v[178:181], v[202:205], v[104:107]
	v_mfma_f32_16x16x32_bf16 v[100:103], v[186:189], v[202:205], v[100:103]
	v_mfma_f32_16x16x32_bf16 v[88:91], v[178:181], v[232:235], v[88:91]
	v_mfma_f32_16x16x32_bf16 v[84:87], v[186:189], v[232:235], v[84:87]
	v_mfma_f32_16x16x32_bf16 v[72:75], v[178:181], v[240:243], v[72:75]
	v_mfma_f32_16x16x32_bf16 v[68:71], v[186:189], v[240:243], v[68:71]
	v_mfma_f32_16x16x32_bf16 v[120:123], v[182:185], v[198:201], v[120:123]
	v_mfma_f32_16x16x32_bf16 v[116:119], v[190:193], v[198:201], v[116:119]
	v_mfma_f32_16x16x32_bf16 v[104:107], v[182:185], v[228:231], v[104:107]
	v_mfma_f32_16x16x32_bf16 v[100:103], v[190:193], v[228:231], v[100:103]
	s_setprio 2
	s_barrier
	v_mfma_f32_16x16x32_bf16 v[88:91], v[182:185], v[236:239], v[88:91]
	v_mfma_f32_16x16x32_bf16 v[84:87], v[190:193], v[236:239], v[84:87]
	v_mfma_f32_16x16x32_bf16 v[72:75], v[182:185], v[244:247], v[72:75]
	v_mfma_f32_16x16x32_bf16 v[68:71], v[190:193], v[244:247], v[68:71]
	s_setprio 0
	s_add_i32 s2, s6, s14
	v_lshl_add_u64 v[212:213], s[4:5], 0, v[136:137]
	s_mov_b32 m0, s2
	ds_read_b128 v[194:197], v161 offset:16384
	ds_read_b128 v[198:201], v161 offset:17408
	ds_read_b128 v[202:205], v161 offset:18432
	ds_read_b128 v[228:231], v161 offset:19456
	ds_read_b128 v[232:235], v161 offset:20480
	ds_read_b128 v[236:239], v161 offset:21504
	ds_read_b128 v[240:243], v161 offset:22528
	ds_read_b128 v[244:247], v161 offset:23552
	global_load_lds_dwordx4 v[212:213], off
	s_add_i32 m0, s2, 0x2000
	s_add_u32 s2, s4, 0x80000
	v_lshl_add_u64 v[214:215], s[4:5], 0, v[132:133]
	s_addc_u32 s3, s5, 0
	s_add_i32 s6, s7, s14
	global_load_lds_dwordx4 v[214:215], off
	v_lshl_add_u64 v[248:249], s[2:3], 0, v[136:137]
	s_mov_b32 m0, s6
	v_lshl_add_u64 v[216:217], s[8:9], 0, v[134:135]
	global_load_lds_dwordx4 v[248:249], off
	v_lshl_add_u64 v[248:249], s[2:3], 0, v[132:133]
	s_add_i32 m0, s6, 0x2000
	s_nop 0
	global_load_lds_dwordx4 v[248:249], off
	v_lshl_add_u64 v[248:249], s[8:9], 0, v[138:139]
	s_mov_b32 m0, s15
	s_nop 0
	global_load_lds_dwordx4 v[248:249], off
	s_mov_b32 m0, s18
	s_nop 0
	global_load_lds_dwordx4 v[216:217], off
	s_waitcnt vmcnt(8)
	s_waitcnt lgkmcnt(0)
	s_barrier
	s_setprio 1
	s_waitcnt lgkmcnt(0)
	v_mfma_f32_16x16x32_bf16 v[64:67], v[146:149], v[194:197], v[64:67]
	v_mfma_f32_16x16x32_bf16 v[60:63], v[170:173], v[194:197], v[60:63]
	v_mfma_f32_16x16x32_bf16 v[48:51], v[146:149], v[202:205], v[48:51]
	v_mfma_f32_16x16x32_bf16 v[44:47], v[170:173], v[202:205], v[44:47]
	v_mfma_f32_16x16x32_bf16 v[32:35], v[146:149], v[232:235], v[32:35]
	v_mfma_f32_16x16x32_bf16 v[28:31], v[170:173], v[232:235], v[28:31]
	v_mfma_f32_16x16x32_bf16 v[16:19], v[146:149], v[240:243], v[16:19]
	v_mfma_f32_16x16x32_bf16 v[12:15], v[170:173], v[240:243], v[12:15]
	v_mfma_f32_16x16x32_bf16 v[64:67], v[166:169], v[198:201], v[64:67]
	v_mfma_f32_16x16x32_bf16 v[60:63], v[174:177], v[198:201], v[60:63]
	v_mfma_f32_16x16x32_bf16 v[48:51], v[166:169], v[228:231], v[48:51]
	v_mfma_f32_16x16x32_bf16 v[44:47], v[174:177], v[228:231], v[44:47]
	v_mfma_f32_16x16x32_bf16 v[32:35], v[166:169], v[236:239], v[32:35]
	v_mfma_f32_16x16x32_bf16 v[28:31], v[174:177], v[236:239], v[28:31]
	v_mfma_f32_16x16x32_bf16 v[16:19], v[166:169], v[244:247], v[16:19]
	v_mfma_f32_16x16x32_bf16 v[12:15], v[174:177], v[244:247], v[12:15]
	s_setprio 0
	s_setprio 1
	v_mfma_f32_16x16x32_bf16 v[56:59], v[178:181], v[194:197], v[56:59]
	v_mfma_f32_16x16x32_bf16 v[52:55], v[186:189], v[194:197], v[52:55]
	v_mfma_f32_16x16x32_bf16 v[40:43], v[178:181], v[202:205], v[40:43]
	v_mfma_f32_16x16x32_bf16 v[36:39], v[186:189], v[202:205], v[36:39]
	v_mfma_f32_16x16x32_bf16 v[24:27], v[178:181], v[232:235], v[24:27]
	v_mfma_f32_16x16x32_bf16 v[20:23], v[186:189], v[232:235], v[20:23]
	v_mfma_f32_16x16x32_bf16 v[6:9], v[178:181], v[240:243], v[6:9]
	v_mfma_f32_16x16x32_bf16 v[2:5], v[186:189], v[240:243], v[2:5]
	v_mfma_f32_16x16x32_bf16 v[56:59], v[182:185], v[198:201], v[56:59]
	v_mfma_f32_16x16x32_bf16 v[52:55], v[190:193], v[198:201], v[52:55]
	v_mfma_f32_16x16x32_bf16 v[40:43], v[182:185], v[228:231], v[40:43]
	v_mfma_f32_16x16x32_bf16 v[36:39], v[190:193], v[228:231], v[36:39]
	s_setprio 2
	s_barrier
	v_mfma_f32_16x16x32_bf16 v[24:27], v[182:185], v[236:239], v[24:27]
	v_mfma_f32_16x16x32_bf16 v[20:23], v[190:193], v[236:239], v[20:23]
	v_mfma_f32_16x16x32_bf16 v[6:9], v[182:185], v[244:247], v[6:9]
	v_mfma_f32_16x16x32_bf16 v[2:5], v[190:193], v[244:247], v[2:5]
	s_setprio 0
	s_add_i32 s6, 0, 0x18000
	s_add_i32 s7, 0, 0x1c000
	v_add_u32_e32 v174, s6, v10
	v_add_u32_e32 v190, s7, v10
	ds_read_b128 v[146:149], v174
	ds_read_b128 v[166:169], v174 offset:1024
	ds_read_b128 v[170:173], v174 offset:2048
	ds_read_b128 v[174:177], v174 offset:3072
	ds_read_b128 v[178:181], v190
	ds_read_b128 v[182:185], v190 offset:1024
	ds_read_b128 v[186:189], v190 offset:2048
	ds_read_b128 v[190:193], v190 offset:3072
	s_add_u32 s2, s8, 0x80000
	s_addc_u32 s3, s9, 0
	s_mov_b32 m0, s19
	v_lshl_add_u64 v[218:219], s[2:3], 0, v[138:139]
	ds_read_b128 v[194:197], v161 offset:32768
	ds_read_b128 v[198:201], v161 offset:33792
	ds_read_b128 v[202:205], v161 offset:34816
	ds_read_b128 v[228:231], v161 offset:35840
	ds_read_b128 v[232:235], v161 offset:36864
	ds_read_b128 v[236:239], v161 offset:37888
	ds_read_b128 v[240:243], v161 offset:38912
	ds_read_b128 v[244:247], v161 offset:39936
	global_load_lds_dwordx4 v[218:219], off
	v_lshl_add_u64 v[218:219], s[2:3], 0, v[134:135]
	s_mov_b32 m0, s30
	s_nop 0
	global_load_lds_dwordx4 v[218:219], off
	s_waitcnt vmcnt(8)
	s_waitcnt lgkmcnt(0)
	s_barrier
	s_setprio 1
	s_waitcnt lgkmcnt(0)
	v_mfma_f32_16x16x32_bf16 v[128:131], v[146:149], v[194:197], v[128:131]
	v_mfma_f32_16x16x32_bf16 v[124:127], v[170:173], v[194:197], v[124:127]
	v_mfma_f32_16x16x32_bf16 v[112:115], v[146:149], v[202:205], v[112:115]
	v_mfma_f32_16x16x32_bf16 v[108:111], v[170:173], v[202:205], v[108:111]
	v_mfma_f32_16x16x32_bf16 v[96:99], v[146:149], v[232:235], v[96:99]
	v_mfma_f32_16x16x32_bf16 v[92:95], v[170:173], v[232:235], v[92:95]
	v_mfma_f32_16x16x32_bf16 v[80:83], v[146:149], v[240:243], v[80:83]
	v_mfma_f32_16x16x32_bf16 v[76:79], v[170:173], v[240:243], v[76:79]
	v_mfma_f32_16x16x32_bf16 v[128:131], v[166:169], v[198:201], v[128:131]
	v_mfma_f32_16x16x32_bf16 v[124:127], v[174:177], v[198:201], v[124:127]
	v_mfma_f32_16x16x32_bf16 v[112:115], v[166:169], v[228:231], v[112:115]
	v_mfma_f32_16x16x32_bf16 v[108:111], v[174:177], v[228:231], v[108:111]
	v_mfma_f32_16x16x32_bf16 v[96:99], v[166:169], v[236:239], v[96:99]
	v_mfma_f32_16x16x32_bf16 v[92:95], v[174:177], v[236:239], v[92:95]
	v_mfma_f32_16x16x32_bf16 v[80:83], v[166:169], v[244:247], v[80:83]
	v_mfma_f32_16x16x32_bf16 v[76:79], v[174:177], v[244:247], v[76:79]
	s_setprio 0
	s_setprio 1
	v_mfma_f32_16x16x32_bf16 v[120:123], v[178:181], v[194:197], v[120:123]
	v_mfma_f32_16x16x32_bf16 v[116:119], v[186:189], v[194:197], v[116:119]
	v_mfma_f32_16x16x32_bf16 v[104:107], v[178:181], v[202:205], v[104:107]
	v_mfma_f32_16x16x32_bf16 v[100:103], v[186:189], v[202:205], v[100:103]
	v_mfma_f32_16x16x32_bf16 v[88:91], v[178:181], v[232:235], v[88:91]
	v_mfma_f32_16x16x32_bf16 v[84:87], v[186:189], v[232:235], v[84:87]
	v_mfma_f32_16x16x32_bf16 v[72:75], v[178:181], v[240:243], v[72:75]
	v_mfma_f32_16x16x32_bf16 v[68:71], v[186:189], v[240:243], v[68:71]
	v_mfma_f32_16x16x32_bf16 v[120:123], v[182:185], v[198:201], v[120:123]
	v_mfma_f32_16x16x32_bf16 v[116:119], v[190:193], v[198:201], v[116:119]
	v_mfma_f32_16x16x32_bf16 v[104:107], v[182:185], v[228:231], v[104:107]
	v_mfma_f32_16x16x32_bf16 v[100:103], v[190:193], v[228:231], v[100:103]
	s_setprio 2
	s_barrier
	v_mfma_f32_16x16x32_bf16 v[88:91], v[182:185], v[236:239], v[88:91]
	v_mfma_f32_16x16x32_bf16 v[84:87], v[190:193], v[236:239], v[84:87]
	v_mfma_f32_16x16x32_bf16 v[72:75], v[182:185], v[244:247], v[72:75]
	v_mfma_f32_16x16x32_bf16 v[68:71], v[190:193], v[244:247], v[68:71]
	s_setprio 0
	s_add_i32 s2, s6, s14
	v_lshl_add_u64 v[212:213], v[212:213], 0, s[86:87]
	s_mov_b32 m0, s2
	ds_read_b128 v[194:197], v161 offset:49152
	ds_read_b128 v[198:201], v161 offset:50176
	ds_read_b128 v[202:205], v161 offset:51200
	ds_read_b128 v[228:231], v161 offset:52224
	ds_read_b128 v[232:235], v161 offset:53248
	ds_read_b128 v[236:239], v161 offset:54272
	ds_read_b128 v[240:243], v161 offset:55296
	ds_read_b128 v[244:247], v161 offset:56320
	global_load_lds_dwordx4 v[212:213], off
	s_add_i32 m0, s2, 0x2000
	s_add_u32 s2, s4, 0x80080
	v_lshl_add_u64 v[212:213], v[214:215], 0, s[86:87]
	s_addc_u32 s3, s5, 0
	s_add_i32 s4, s7, s14
	global_load_lds_dwordx4 v[212:213], off
	v_lshl_add_u64 v[212:213], s[2:3], 0, v[136:137]
	s_mov_b32 m0, s4
	s_nop 0
	global_load_lds_dwordx4 v[212:213], off
	v_lshl_add_u64 v[212:213], s[2:3], 0, v[132:133]
	s_add_i32 m0, s4, 0x2000
	s_nop 0
	global_load_lds_dwordx4 v[212:213], off
	v_lshl_add_u64 v[212:213], v[248:249], 0, s[86:87]
	s_mov_b32 m0, s31
	s_nop 0
	global_load_lds_dwordx4 v[212:213], off
	v_lshl_add_u64 v[212:213], v[216:217], 0, s[86:87]
	s_mov_b32 m0, s34
	s_nop 0
	global_load_lds_dwordx4 v[212:213], off
	s_waitcnt vmcnt(8)
	s_waitcnt lgkmcnt(0)
	s_barrier
	s_setprio 1
	s_waitcnt lgkmcnt(0)
	v_mfma_f32_16x16x32_bf16 v[64:67], v[146:149], v[194:197], v[64:67]
	v_mfma_f32_16x16x32_bf16 v[60:63], v[170:173], v[194:197], v[60:63]
	v_mfma_f32_16x16x32_bf16 v[48:51], v[146:149], v[202:205], v[48:51]
	v_mfma_f32_16x16x32_bf16 v[44:47], v[170:173], v[202:205], v[44:47]
	v_mfma_f32_16x16x32_bf16 v[32:35], v[146:149], v[232:235], v[32:35]
	v_mfma_f32_16x16x32_bf16 v[28:31], v[170:173], v[232:235], v[28:31]
	v_mfma_f32_16x16x32_bf16 v[16:19], v[146:149], v[240:243], v[16:19]
	v_mfma_f32_16x16x32_bf16 v[12:15], v[170:173], v[240:243], v[12:15]
	v_mfma_f32_16x16x32_bf16 v[64:67], v[166:169], v[198:201], v[64:67]
	v_mfma_f32_16x16x32_bf16 v[60:63], v[174:177], v[198:201], v[60:63]
	v_mfma_f32_16x16x32_bf16 v[48:51], v[166:169], v[228:231], v[48:51]
	v_mfma_f32_16x16x32_bf16 v[44:47], v[174:177], v[228:231], v[44:47]
	v_mfma_f32_16x16x32_bf16 v[32:35], v[166:169], v[236:239], v[32:35]
	v_mfma_f32_16x16x32_bf16 v[28:31], v[174:177], v[236:239], v[28:31]
	v_mfma_f32_16x16x32_bf16 v[16:19], v[166:169], v[244:247], v[16:19]
	v_mfma_f32_16x16x32_bf16 v[12:15], v[174:177], v[244:247], v[12:15]
	s_setprio 0
	s_setprio 1
	v_mfma_f32_16x16x32_bf16 v[56:59], v[178:181], v[194:197], v[56:59]
	v_mfma_f32_16x16x32_bf16 v[52:55], v[186:189], v[194:197], v[52:55]
	v_mfma_f32_16x16x32_bf16 v[40:43], v[178:181], v[202:205], v[40:43]
	v_mfma_f32_16x16x32_bf16 v[36:39], v[186:189], v[202:205], v[36:39]
	v_mfma_f32_16x16x32_bf16 v[24:27], v[178:181], v[232:235], v[24:27]
	v_mfma_f32_16x16x32_bf16 v[20:23], v[186:189], v[232:235], v[20:23]
	v_mfma_f32_16x16x32_bf16 v[6:9], v[178:181], v[240:243], v[6:9]
	v_mfma_f32_16x16x32_bf16 v[2:5], v[186:189], v[240:243], v[2:5]
	v_mfma_f32_16x16x32_bf16 v[56:59], v[182:185], v[198:201], v[56:59]
	v_mfma_f32_16x16x32_bf16 v[52:55], v[190:193], v[198:201], v[52:55]
	v_mfma_f32_16x16x32_bf16 v[40:43], v[182:185], v[228:231], v[40:43]
	v_mfma_f32_16x16x32_bf16 v[36:39], v[190:193], v[228:231], v[36:39]
	s_setprio 2
	s_barrier
	v_mfma_f32_16x16x32_bf16 v[24:27], v[182:185], v[236:239], v[24:27]
	v_mfma_f32_16x16x32_bf16 v[20:23], v[190:193], v[236:239], v[20:23]
	v_mfma_f32_16x16x32_bf16 v[6:9], v[182:185], v[244:247], v[6:9]
	v_mfma_f32_16x16x32_bf16 v[2:5], v[190:193], v[244:247], v[2:5]
	s_setprio 0
	s_add_i32 s48, s48, 2
	s_add_u32 s0, s0, 0x100
	s_addc_u32 s1, s1, 0
	s_add_u32 s46, s46, 0x100
	s_addc_u32 s47, s47, 0
	s_cmp_gt_u32 s48, 29
	s_cbranch_scc0 .LBB0_262
	s_and_b64 vcc, exec, s[28:29]
	s_cbranch_vccz .LBB0_265
	s_barrier

.LBB0_986:
	s_add_u32 s4, s0, 0x100
	s_addc_u32 s5, s1, 0
	s_add_i32 s2, 0, 0x10000
	s_cmpk_eq_i32 s49, 0x54
	s_cselect_b32 s11, s41, s5
	s_cselect_b32 s10, s40, s4
	v_add_u32_e32 v148, s2, v10
	s_cselect_b32 s9, s45, s48
	s_cselect_b32 s8, s44, s33
	s_add_i32 s3, 0, 0x14000
	ds_read_b128 v[144:147], v148
	ds_read_b128 v[166:169], v148 offset:1024
	ds_read_b128 v[170:173], v148 offset:2048
	ds_read_b128 v[174:177], v148 offset:3072
	v_add_u32_e32 v148, s3, v10
	ds_read_b128 v[178:181], v148
	ds_read_b128 v[182:185], v148 offset:1024
	ds_read_b128 v[186:189], v148 offset:2048
	ds_read_b128 v[190:193], v148 offset:3072
	v_lshl_add_u64 v[148:149], s[0:1], 0, v[140:141]
	s_add_i32 m0, s15, 0xc000
	ds_read_b128 v[194:197], v161
	ds_read_b128 v[198:201], v161 offset:1024
	ds_read_b128 v[202:205], v161 offset:2048
	ds_read_b128 v[228:231], v161 offset:3072
	ds_read_b128 v[232:235], v161 offset:4096
	ds_read_b128 v[236:239], v161 offset:5120
	ds_read_b128 v[240:243], v161 offset:6144
	ds_read_b128 v[244:247], v161 offset:7168
	global_load_lds_dwordx4 v[148:149], off
	v_lshl_add_u64 v[148:149], s[0:1], 0, v[142:143]
	s_add_i32 m0, s15, 0xe000
	s_nop 0
	global_load_lds_dwordx4 v[148:149], off
	s_waitcnt vmcnt(8)
	s_waitcnt lgkmcnt(0)
	s_barrier
	s_setprio 1
	s_waitcnt lgkmcnt(0)
	v_mfma_f32_16x16x32_bf16 v[128:131], v[144:147], v[194:197], v[128:131]
	v_mfma_f32_16x16x32_bf16 v[124:127], v[170:173], v[194:197], v[124:127]
	v_mfma_f32_16x16x32_bf16 v[112:115], v[144:147], v[202:205], v[112:115]
	v_mfma_f32_16x16x32_bf16 v[108:111], v[170:173], v[202:205], v[108:111]
	v_mfma_f32_16x16x32_bf16 v[96:99], v[144:147], v[232:235], v[96:99]
	v_mfma_f32_16x16x32_bf16 v[92:95], v[170:173], v[232:235], v[92:95]
	v_mfma_f32_16x16x32_bf16 v[80:83], v[144:147], v[240:243], v[80:83]
	v_mfma_f32_16x16x32_bf16 v[76:79], v[170:173], v[240:243], v[76:79]
	v_mfma_f32_16x16x32_bf16 v[128:131], v[166:169], v[198:201], v[128:131]
	v_mfma_f32_16x16x32_bf16 v[124:127], v[174:177], v[198:201], v[124:127]
	v_mfma_f32_16x16x32_bf16 v[112:115], v[166:169], v[228:231], v[112:115]
	v_mfma_f32_16x16x32_bf16 v[108:111], v[174:177], v[228:231], v[108:111]
	v_mfma_f32_16x16x32_bf16 v[96:99], v[166:169], v[236:239], v[96:99]
	v_mfma_f32_16x16x32_bf16 v[92:95], v[174:177], v[236:239], v[92:95]
	v_mfma_f32_16x16x32_bf16 v[80:83], v[166:169], v[244:247], v[80:83]
	v_mfma_f32_16x16x32_bf16 v[76:79], v[174:177], v[244:247], v[76:79]
	s_setprio 0
	s_setprio 1
	v_mfma_f32_16x16x32_bf16 v[120:123], v[178:181], v[194:197], v[120:123]
	v_mfma_f32_16x16x32_bf16 v[116:119], v[186:189], v[194:197], v[116:119]
	v_mfma_f32_16x16x32_bf16 v[104:107], v[178:181], v[202:205], v[104:107]
	v_mfma_f32_16x16x32_bf16 v[100:103], v[186:189], v[202:205], v[100:103]
	v_mfma_f32_16x16x32_bf16 v[88:91], v[178:181], v[232:235], v[88:91]
	v_mfma_f32_16x16x32_bf16 v[84:87], v[186:189], v[232:235], v[84:87]
	v_mfma_f32_16x16x32_bf16 v[72:75], v[178:181], v[240:243], v[72:75]
	v_mfma_f32_16x16x32_bf16 v[68:71], v[186:189], v[240:243], v[68:71]
	v_mfma_f32_16x16x32_bf16 v[120:123], v[182:185], v[198:201], v[120:123]
	v_mfma_f32_16x16x32_bf16 v[116:119], v[190:193], v[198:201], v[116:119]
	v_mfma_f32_16x16x32_bf16 v[104:107], v[182:185], v[228:231], v[104:107]
	v_mfma_f32_16x16x32_bf16 v[100:103], v[190:193], v[228:231], v[100:103]
	s_setprio 2
	s_barrier
	v_mfma_f32_16x16x32_bf16 v[88:91], v[182:185], v[236:239], v[88:91]
	v_mfma_f32_16x16x32_bf16 v[84:87], v[190:193], v[236:239], v[84:87]
	v_mfma_f32_16x16x32_bf16 v[72:75], v[182:185], v[244:247], v[72:75]
	v_mfma_f32_16x16x32_bf16 v[68:71], v[190:193], v[244:247], v[68:71]
	s_setprio 0
	s_add_i32 s0, s2, s14
	v_lshl_add_u64 v[148:149], s[8:9], 0, v[136:137]
	s_mov_b32 m0, s0
	ds_read_b128 v[194:197], v161 offset:16384
	ds_read_b128 v[198:201], v161 offset:17408
	ds_read_b128 v[202:205], v161 offset:18432
	ds_read_b128 v[228:231], v161 offset:19456
	ds_read_b128 v[232:235], v161 offset:20480
	ds_read_b128 v[236:239], v161 offset:21504
	ds_read_b128 v[240:243], v161 offset:22528
	ds_read_b128 v[244:247], v161 offset:23552
	global_load_lds_dwordx4 v[148:149], off
	s_add_i32 m0, s0, 0x2000
	s_add_u32 s0, s8, 0x160000
	v_lshl_add_u64 v[212:213], s[8:9], 0, v[132:133]
	s_addc_u32 s1, s9, 0
	s_add_i32 s2, s3, s14
	global_load_lds_dwordx4 v[212:213], off
	v_lshl_add_u64 v[214:215], s[0:1], 0, v[136:137]
	s_mov_b32 m0, s2
	v_lshl_add_u64 v[216:217], s[10:11], 0, v[134:135]
	global_load_lds_dwordx4 v[214:215], off
	v_lshl_add_u64 v[214:215], s[0:1], 0, v[132:133]
	s_add_i32 m0, s2, 0x2000
	s_nop 0
	global_load_lds_dwordx4 v[214:215], off
	v_lshl_add_u64 v[214:215], s[10:11], 0, v[138:139]
	s_mov_b32 m0, s15
	s_nop 0
	global_load_lds_dwordx4 v[214:215], off
	s_mov_b32 m0, s18
	s_nop 0
	global_load_lds_dwordx4 v[216:217], off
	s_waitcnt vmcnt(8)
	s_waitcnt lgkmcnt(0)
	s_barrier
	s_setprio 1
	s_waitcnt lgkmcnt(0)
	v_mfma_f32_16x16x32_bf16 v[64:67], v[144:147], v[194:197], v[64:67]
	v_mfma_f32_16x16x32_bf16 v[60:63], v[170:173], v[194:197], v[60:63]
	v_mfma_f32_16x16x32_bf16 v[48:51], v[144:147], v[202:205], v[48:51]
	v_mfma_f32_16x16x32_bf16 v[44:47], v[170:173], v[202:205], v[44:47]
	v_mfma_f32_16x16x32_bf16 v[32:35], v[144:147], v[232:235], v[32:35]
	v_mfma_f32_16x16x32_bf16 v[28:31], v[170:173], v[232:235], v[28:31]
	v_mfma_f32_16x16x32_bf16 v[16:19], v[144:147], v[240:243], v[16:19]
	v_mfma_f32_16x16x32_bf16 v[12:15], v[170:173], v[240:243], v[12:15]
	v_mfma_f32_16x16x32_bf16 v[64:67], v[166:169], v[198:201], v[64:67]
	v_mfma_f32_16x16x32_bf16 v[60:63], v[174:177], v[198:201], v[60:63]
	v_mfma_f32_16x16x32_bf16 v[48:51], v[166:169], v[228:231], v[48:51]
	v_mfma_f32_16x16x32_bf16 v[44:47], v[174:177], v[228:231], v[44:47]
	v_mfma_f32_16x16x32_bf16 v[32:35], v[166:169], v[236:239], v[32:35]
	v_mfma_f32_16x16x32_bf16 v[28:31], v[174:177], v[236:239], v[28:31]
	v_mfma_f32_16x16x32_bf16 v[16:19], v[166:169], v[244:247], v[16:19]
	v_mfma_f32_16x16x32_bf16 v[12:15], v[174:177], v[244:247], v[12:15]
	s_setprio 0
	s_setprio 1
	v_mfma_f32_16x16x32_bf16 v[56:59], v[178:181], v[194:197], v[56:59]
	v_mfma_f32_16x16x32_bf16 v[52:55], v[186:189], v[194:197], v[52:55]
	v_mfma_f32_16x16x32_bf16 v[40:43], v[178:181], v[202:205], v[40:43]
	v_mfma_f32_16x16x32_bf16 v[36:39], v[186:189], v[202:205], v[36:39]
	v_mfma_f32_16x16x32_bf16 v[24:27], v[178:181], v[232:235], v[24:27]
	v_mfma_f32_16x16x32_bf16 v[20:23], v[186:189], v[232:235], v[20:23]
	v_mfma_f32_16x16x32_bf16 v[6:9], v[178:181], v[240:243], v[6:9]
	v_mfma_f32_16x16x32_bf16 v[2:5], v[186:189], v[240:243], v[2:5]
	v_mfma_f32_16x16x32_bf16 v[56:59], v[182:185], v[198:201], v[56:59]
	v_mfma_f32_16x16x32_bf16 v[52:55], v[190:193], v[198:201], v[52:55]
	v_mfma_f32_16x16x32_bf16 v[40:43], v[182:185], v[228:231], v[40:43]
	v_mfma_f32_16x16x32_bf16 v[36:39], v[190:193], v[228:231], v[36:39]
	s_setprio 2
	s_barrier
	v_mfma_f32_16x16x32_bf16 v[24:27], v[182:185], v[236:239], v[24:27]
	v_mfma_f32_16x16x32_bf16 v[20:23], v[190:193], v[236:239], v[20:23]
	v_mfma_f32_16x16x32_bf16 v[6:9], v[182:185], v[244:247], v[6:9]
	v_mfma_f32_16x16x32_bf16 v[2:5], v[190:193], v[244:247], v[2:5]
	s_setprio 0
	s_add_i32 s2, 0, 0x18000
	s_add_i32 s3, 0, 0x1c000
	v_add_u32_e32 v174, s2, v10
	v_add_u32_e32 v190, s3, v10
	ds_read_b128 v[144:147], v174
	ds_read_b128 v[166:169], v174 offset:1024
	ds_read_b128 v[170:173], v174 offset:2048
	ds_read_b128 v[174:177], v174 offset:3072
	ds_read_b128 v[178:181], v190
	ds_read_b128 v[182:185], v190 offset:1024
	ds_read_b128 v[186:189], v190 offset:2048
	ds_read_b128 v[190:193], v190 offset:3072
	s_add_u32 s0, s10, 0x160000
	s_addc_u32 s1, s11, 0
	s_mov_b32 m0, s19
	v_lshl_add_u64 v[218:219], s[0:1], 0, v[138:139]
	ds_read_b128 v[194:197], v161 offset:32768
	ds_read_b128 v[198:201], v161 offset:33792
	ds_read_b128 v[202:205], v161 offset:34816
	ds_read_b128 v[228:231], v161 offset:35840
	ds_read_b128 v[232:235], v161 offset:36864
	ds_read_b128 v[236:239], v161 offset:37888
	ds_read_b128 v[240:243], v161 offset:38912
	ds_read_b128 v[244:247], v161 offset:39936
	global_load_lds_dwordx4 v[218:219], off
	v_lshl_add_u64 v[218:219], s[0:1], 0, v[134:135]
	s_mov_b32 m0, s22
	s_nop 0
	global_load_lds_dwordx4 v[218:219], off
	s_waitcnt vmcnt(8)
	s_waitcnt lgkmcnt(0)
	s_barrier
	s_setprio 1
	s_waitcnt lgkmcnt(0)
	v_mfma_f32_16x16x32_bf16 v[128:131], v[144:147], v[194:197], v[128:131]
	v_mfma_f32_16x16x32_bf16 v[124:127], v[170:173], v[194:197], v[124:127]
	v_mfma_f32_16x16x32_bf16 v[112:115], v[144:147], v[202:205], v[112:115]
	v_mfma_f32_16x16x32_bf16 v[108:111], v[170:173], v[202:205], v[108:111]
	v_mfma_f32_16x16x32_bf16 v[96:99], v[144:147], v[232:235], v[96:99]
	v_mfma_f32_16x16x32_bf16 v[92:95], v[170:173], v[232:235], v[92:95]
	v_mfma_f32_16x16x32_bf16 v[80:83], v[144:147], v[240:243], v[80:83]
	v_mfma_f32_16x16x32_bf16 v[76:79], v[170:173], v[240:243], v[76:79]
	v_mfma_f32_16x16x32_bf16 v[128:131], v[166:169], v[198:201], v[128:131]
	v_mfma_f32_16x16x32_bf16 v[124:127], v[174:177], v[198:201], v[124:127]
	v_mfma_f32_16x16x32_bf16 v[112:115], v[166:169], v[228:231], v[112:115]
	v_mfma_f32_16x16x32_bf16 v[108:111], v[174:177], v[228:231], v[108:111]
	v_mfma_f32_16x16x32_bf16 v[96:99], v[166:169], v[236:239], v[96:99]
	v_mfma_f32_16x16x32_bf16 v[92:95], v[174:177], v[236:239], v[92:95]
	v_mfma_f32_16x16x32_bf16 v[80:83], v[166:169], v[244:247], v[80:83]
	v_mfma_f32_16x16x32_bf16 v[76:79], v[174:177], v[244:247], v[76:79]
	s_setprio 0
	s_setprio 1
	v_mfma_f32_16x16x32_bf16 v[120:123], v[178:181], v[194:197], v[120:123]
	v_mfma_f32_16x16x32_bf16 v[116:119], v[186:189], v[194:197], v[116:119]
	v_mfma_f32_16x16x32_bf16 v[104:107], v[178:181], v[202:205], v[104:107]
	v_mfma_f32_16x16x32_bf16 v[100:103], v[186:189], v[202:205], v[100:103]
	v_mfma_f32_16x16x32_bf16 v[88:91], v[178:181], v[232:235], v[88:91]
	v_mfma_f32_16x16x32_bf16 v[84:87], v[186:189], v[232:235], v[84:87]
	v_mfma_f32_16x16x32_bf16 v[72:75], v[178:181], v[240:243], v[72:75]
	v_mfma_f32_16x16x32_bf16 v[68:71], v[186:189], v[240:243], v[68:71]
	v_mfma_f32_16x16x32_bf16 v[120:123], v[182:185], v[198:201], v[120:123]
	v_mfma_f32_16x16x32_bf16 v[116:119], v[190:193], v[198:201], v[116:119]
	v_mfma_f32_16x16x32_bf16 v[104:107], v[182:185], v[228:231], v[104:107]
	v_mfma_f32_16x16x32_bf16 v[100:103], v[190:193], v[228:231], v[100:103]
	s_setprio 2
	s_barrier
	v_mfma_f32_16x16x32_bf16 v[88:91], v[182:185], v[236:239], v[88:91]
	v_mfma_f32_16x16x32_bf16 v[84:87], v[190:193], v[236:239], v[84:87]
	v_mfma_f32_16x16x32_bf16 v[72:75], v[182:185], v[244:247], v[72:75]
	v_mfma_f32_16x16x32_bf16 v[68:71], v[190:193], v[244:247], v[68:71]
	s_setprio 0
	s_add_i32 s0, s2, s14
	v_lshl_add_u64 v[148:149], v[148:149], 0, s[86:87]
	s_mov_b32 m0, s0
	ds_read_b128 v[194:197], v161 offset:49152
	ds_read_b128 v[198:201], v161 offset:50176
	ds_read_b128 v[202:205], v161 offset:51200
	ds_read_b128 v[228:231], v161 offset:52224
	ds_read_b128 v[232:235], v161 offset:53248
	ds_read_b128 v[236:239], v161 offset:54272
	ds_read_b128 v[240:243], v161 offset:55296
	ds_read_b128 v[244:247], v161 offset:56320
	global_load_lds_dwordx4 v[148:149], off
	s_add_i32 m0, s0, 0x2000
	s_add_u32 s0, s8, 0x160080
	v_lshl_add_u64 v[148:149], v[212:213], 0, s[86:87]
	s_addc_u32 s1, s9, 0
	s_add_i32 s2, s3, s14
	global_load_lds_dwordx4 v[148:149], off
	v_lshl_add_u64 v[148:149], s[0:1], 0, v[136:137]
	s_mov_b32 m0, s2
	s_nop 0
	global_load_lds_dwordx4 v[148:149], off
	v_lshl_add_u64 v[148:149], s[0:1], 0, v[132:133]
	s_add_i32 m0, s2, 0x2000
	s_nop 0
	global_load_lds_dwordx4 v[148:149], off
	v_lshl_add_u64 v[148:149], v[214:215], 0, s[86:87]
	s_mov_b32 m0, s31
	s_nop 0
	global_load_lds_dwordx4 v[148:149], off
	v_lshl_add_u64 v[148:149], v[216:217], 0, s[86:87]
	s_mov_b32 m0, s34
	s_nop 0
	global_load_lds_dwordx4 v[148:149], off
	s_waitcnt vmcnt(8)
	s_waitcnt lgkmcnt(0)
	s_barrier
	s_setprio 1
	s_waitcnt lgkmcnt(0)
	v_mfma_f32_16x16x32_bf16 v[64:67], v[144:147], v[194:197], v[64:67]
	v_mfma_f32_16x16x32_bf16 v[60:63], v[170:173], v[194:197], v[60:63]
	v_mfma_f32_16x16x32_bf16 v[48:51], v[144:147], v[202:205], v[48:51]
	v_mfma_f32_16x16x32_bf16 v[44:47], v[170:173], v[202:205], v[44:47]
	v_mfma_f32_16x16x32_bf16 v[32:35], v[144:147], v[232:235], v[32:35]
	v_mfma_f32_16x16x32_bf16 v[28:31], v[170:173], v[232:235], v[28:31]
	v_mfma_f32_16x16x32_bf16 v[16:19], v[144:147], v[240:243], v[16:19]
	v_mfma_f32_16x16x32_bf16 v[12:15], v[170:173], v[240:243], v[12:15]
	v_mfma_f32_16x16x32_bf16 v[64:67], v[166:169], v[198:201], v[64:67]
	v_mfma_f32_16x16x32_bf16 v[60:63], v[174:177], v[198:201], v[60:63]
	v_mfma_f32_16x16x32_bf16 v[48:51], v[166:169], v[228:231], v[48:51]
	v_mfma_f32_16x16x32_bf16 v[44:47], v[174:177], v[228:231], v[44:47]
	v_mfma_f32_16x16x32_bf16 v[32:35], v[166:169], v[236:239], v[32:35]
	v_mfma_f32_16x16x32_bf16 v[28:31], v[174:177], v[236:239], v[28:31]
	v_mfma_f32_16x16x32_bf16 v[16:19], v[166:169], v[244:247], v[16:19]
	v_mfma_f32_16x16x32_bf16 v[12:15], v[174:177], v[244:247], v[12:15]
	s_setprio 0
	s_setprio 1
	v_mfma_f32_16x16x32_bf16 v[56:59], v[178:181], v[194:197], v[56:59]
	v_mfma_f32_16x16x32_bf16 v[52:55], v[186:189], v[194:197], v[52:55]
	v_mfma_f32_16x16x32_bf16 v[40:43], v[178:181], v[202:205], v[40:43]
	v_mfma_f32_16x16x32_bf16 v[36:39], v[186:189], v[202:205], v[36:39]
	v_mfma_f32_16x16x32_bf16 v[24:27], v[178:181], v[232:235], v[24:27]
	v_mfma_f32_16x16x32_bf16 v[20:23], v[186:189], v[232:235], v[20:23]
	v_mfma_f32_16x16x32_bf16 v[6:9], v[178:181], v[240:243], v[6:9]
	v_mfma_f32_16x16x32_bf16 v[2:5], v[186:189], v[240:243], v[2:5]
	v_mfma_f32_16x16x32_bf16 v[56:59], v[182:185], v[198:201], v[56:59]
	v_mfma_f32_16x16x32_bf16 v[52:55], v[190:193], v[198:201], v[52:55]
	v_mfma_f32_16x16x32_bf16 v[40:43], v[182:185], v[228:231], v[40:43]
	v_mfma_f32_16x16x32_bf16 v[36:39], v[190:193], v[228:231], v[36:39]
	s_setprio 2
	s_barrier
	v_mfma_f32_16x16x32_bf16 v[24:27], v[182:185], v[236:239], v[24:27]
	v_mfma_f32_16x16x32_bf16 v[20:23], v[190:193], v[236:239], v[20:23]
	v_mfma_f32_16x16x32_bf16 v[6:9], v[182:185], v[244:247], v[6:9]
	v_mfma_f32_16x16x32_bf16 v[2:5], v[190:193], v[244:247], v[2:5]
	s_setprio 0
	s_add_i32 s49, s49, 2
	s_add_u32 s33, s33, 0x100
	s_addc_u32 s48, s48, 0
	s_cmpk_gt_u32 s49, 0x55
	s_mov_b64 s[0:1], s[4:5]
	s_cbranch_scc0 .LBB0_986
	s_and_b64 vcc, exec, s[42:43]
	s_cbranch_vccz .LBB0_989
	s_barrier

.LBB0_1077:
	s_add_u32 s2, s30, 0xfff80080
	s_addc_u32 s3, s31, -1
	s_add_i32 s6, 0, 0x10000
	s_cmp_eq_u32 s61, 28
	s_cselect_b32 s41, s11, s3
	s_cselect_b32 s40, s19, s2
	v_add_u32_e32 v148, s6, v10
	s_cselect_b32 s35, s9, s60
	s_cselect_b32 s34, s29, s59
	s_add_i32 s7, 0, 0x14000
	ds_read_b128 v[166:169], v148
	ds_read_b128 v[170:173], v148 offset:1024
	ds_read_b128 v[174:177], v148 offset:2048
	ds_read_b128 v[178:181], v148 offset:3072
	v_add_u32_e32 v148, s7, v10
	ds_read_b128 v[182:185], v148
	ds_read_b128 v[186:189], v148 offset:1024
	ds_read_b128 v[190:193], v148 offset:2048
	ds_read_b128 v[194:197], v148 offset:3072
	v_lshl_add_u64 v[148:149], s[30:31], 0, v[144:145]
	s_add_i32 m0, s48, 0xc000
	ds_read_b128 v[198:201], v161
	ds_read_b128 v[202:205], v161 offset:1024
	ds_read_b128 v[228:231], v161 offset:2048
	ds_read_b128 v[232:235], v161 offset:3072
	ds_read_b128 v[236:239], v161 offset:4096
	ds_read_b128 v[240:243], v161 offset:5120
	ds_read_b128 v[244:247], v161 offset:6144
	ds_read_b128 v[212:215], v161 offset:7168
	global_load_lds_dwordx4 v[148:149], off
	v_lshl_add_u64 v[148:149], s[30:31], 0, v[146:147]
	s_add_i32 m0, s48, 0xe000
	s_nop 0
	global_load_lds_dwordx4 v[148:149], off
	s_waitcnt vmcnt(8)
	s_waitcnt lgkmcnt(0)
	s_barrier
	s_setprio 1
	s_waitcnt lgkmcnt(0)
	v_mfma_f32_16x16x32_bf16 v[128:131], v[166:169], v[198:201], v[128:131]
	v_mfma_f32_16x16x32_bf16 v[124:127], v[174:177], v[198:201], v[124:127]
	v_mfma_f32_16x16x32_bf16 v[112:115], v[166:169], v[228:231], v[112:115]
	v_mfma_f32_16x16x32_bf16 v[108:111], v[174:177], v[228:231], v[108:111]
	v_mfma_f32_16x16x32_bf16 v[96:99], v[166:169], v[236:239], v[96:99]
	v_mfma_f32_16x16x32_bf16 v[92:95], v[174:177], v[236:239], v[92:95]
	v_mfma_f32_16x16x32_bf16 v[80:83], v[166:169], v[244:247], v[80:83]
	v_mfma_f32_16x16x32_bf16 v[76:79], v[174:177], v[244:247], v[76:79]
	v_mfma_f32_16x16x32_bf16 v[128:131], v[170:173], v[202:205], v[128:131]
	v_mfma_f32_16x16x32_bf16 v[124:127], v[178:181], v[202:205], v[124:127]
	v_mfma_f32_16x16x32_bf16 v[112:115], v[170:173], v[232:235], v[112:115]
	v_mfma_f32_16x16x32_bf16 v[108:111], v[178:181], v[232:235], v[108:111]
	v_mfma_f32_16x16x32_bf16 v[96:99], v[170:173], v[240:243], v[96:99]
	v_mfma_f32_16x16x32_bf16 v[92:95], v[178:181], v[240:243], v[92:95]
	v_mfma_f32_16x16x32_bf16 v[80:83], v[170:173], v[212:215], v[80:83]
	v_mfma_f32_16x16x32_bf16 v[76:79], v[178:181], v[212:215], v[76:79]
	s_setprio 0
	s_setprio 1
	v_mfma_f32_16x16x32_bf16 v[120:123], v[182:185], v[198:201], v[120:123]
	v_mfma_f32_16x16x32_bf16 v[116:119], v[190:193], v[198:201], v[116:119]
	v_mfma_f32_16x16x32_bf16 v[104:107], v[182:185], v[228:231], v[104:107]
	v_mfma_f32_16x16x32_bf16 v[100:103], v[190:193], v[228:231], v[100:103]
	v_mfma_f32_16x16x32_bf16 v[88:91], v[182:185], v[236:239], v[88:91]
	v_mfma_f32_16x16x32_bf16 v[84:87], v[190:193], v[236:239], v[84:87]
	v_mfma_f32_16x16x32_bf16 v[72:75], v[182:185], v[244:247], v[72:75]
	v_mfma_f32_16x16x32_bf16 v[68:71], v[190:193], v[244:247], v[68:71]
	v_mfma_f32_16x16x32_bf16 v[120:123], v[186:189], v[202:205], v[120:123]
	v_mfma_f32_16x16x32_bf16 v[116:119], v[194:197], v[202:205], v[116:119]
	v_mfma_f32_16x16x32_bf16 v[104:107], v[186:189], v[232:235], v[104:107]
	v_mfma_f32_16x16x32_bf16 v[100:103], v[194:197], v[232:235], v[100:103]
	s_setprio 2
	s_barrier
	v_mfma_f32_16x16x32_bf16 v[88:91], v[186:189], v[240:243], v[88:91]
	v_mfma_f32_16x16x32_bf16 v[84:87], v[194:197], v[240:243], v[84:87]
	v_mfma_f32_16x16x32_bf16 v[72:75], v[186:189], v[212:215], v[72:75]
	v_mfma_f32_16x16x32_bf16 v[68:71], v[194:197], v[212:215], v[68:71]
	s_setprio 0
	s_add_i32 s2, s6, s47
	v_lshl_add_u64 v[148:149], s[34:35], 0, v[134:135]
	s_mov_b32 m0, s2
	ds_read_b128 v[198:201], v161 offset:16384
	ds_read_b128 v[202:205], v161 offset:17408
	ds_read_b128 v[212:215], v161 offset:18432
	ds_read_b128 v[228:231], v161 offset:19456
	ds_read_b128 v[232:235], v161 offset:20480
	ds_read_b128 v[236:239], v161 offset:21504
	ds_read_b128 v[240:243], v161 offset:22528
	ds_read_b128 v[244:247], v161 offset:23552
	global_load_lds_dwordx4 v[148:149], off
	s_add_i32 m0, s2, 0x2000
	s_add_u32 s2, s34, 0x80000
	v_lshl_add_u64 v[216:217], s[34:35], 0, v[138:139]
	s_addc_u32 s3, s35, 0
	s_add_i32 s6, s7, s47
	global_load_lds_dwordx4 v[216:217], off
	v_lshl_add_u64 v[218:219], s[2:3], 0, v[134:135]
	s_mov_b32 m0, s6
	v_lshl_add_u64 v[248:249], s[40:41], 0, v[136:137]
	global_load_lds_dwordx4 v[218:219], off
	v_lshl_add_u64 v[218:219], s[2:3], 0, v[138:139]
	s_add_i32 m0, s6, 0x2000
	s_nop 0
	global_load_lds_dwordx4 v[218:219], off
	v_lshl_add_u64 v[218:219], s[40:41], 0, v[132:133]
	s_mov_b32 m0, s48
	s_nop 0
	global_load_lds_dwordx4 v[218:219], off
	s_mov_b32 m0, s49
	s_nop 0
	global_load_lds_dwordx4 v[248:249], off
	s_waitcnt vmcnt(8)
	s_waitcnt lgkmcnt(0)
	s_barrier
	s_setprio 1
	s_waitcnt lgkmcnt(0)
	v_mfma_f32_16x16x32_bf16 v[64:67], v[166:169], v[198:201], v[64:67]
	v_mfma_f32_16x16x32_bf16 v[60:63], v[174:177], v[198:201], v[60:63]
	v_mfma_f32_16x16x32_bf16 v[48:51], v[166:169], v[212:215], v[48:51]
	v_mfma_f32_16x16x32_bf16 v[44:47], v[174:177], v[212:215], v[44:47]
	v_mfma_f32_16x16x32_bf16 v[32:35], v[166:169], v[232:235], v[32:35]
	v_mfma_f32_16x16x32_bf16 v[28:31], v[174:177], v[232:235], v[28:31]
	v_mfma_f32_16x16x32_bf16 v[16:19], v[166:169], v[240:243], v[16:19]
	v_mfma_f32_16x16x32_bf16 v[12:15], v[174:177], v[240:243], v[12:15]
	v_mfma_f32_16x16x32_bf16 v[64:67], v[170:173], v[202:205], v[64:67]
	v_mfma_f32_16x16x32_bf16 v[60:63], v[178:181], v[202:205], v[60:63]
	v_mfma_f32_16x16x32_bf16 v[48:51], v[170:173], v[228:231], v[48:51]
	v_mfma_f32_16x16x32_bf16 v[44:47], v[178:181], v[228:231], v[44:47]
	v_mfma_f32_16x16x32_bf16 v[32:35], v[170:173], v[236:239], v[32:35]
	v_mfma_f32_16x16x32_bf16 v[28:31], v[178:181], v[236:239], v[28:31]
	v_mfma_f32_16x16x32_bf16 v[16:19], v[170:173], v[244:247], v[16:19]
	v_mfma_f32_16x16x32_bf16 v[12:15], v[178:181], v[244:247], v[12:15]
	s_setprio 0
	s_setprio 1
	v_mfma_f32_16x16x32_bf16 v[56:59], v[182:185], v[198:201], v[56:59]
	v_mfma_f32_16x16x32_bf16 v[52:55], v[190:193], v[198:201], v[52:55]
	v_mfma_f32_16x16x32_bf16 v[40:43], v[182:185], v[212:215], v[40:43]
	v_mfma_f32_16x16x32_bf16 v[36:39], v[190:193], v[212:215], v[36:39]
	v_mfma_f32_16x16x32_bf16 v[24:27], v[182:185], v[232:235], v[24:27]
	v_mfma_f32_16x16x32_bf16 v[20:23], v[190:193], v[232:235], v[20:23]
	v_mfma_f32_16x16x32_bf16 v[6:9], v[182:185], v[240:243], v[6:9]
	v_mfma_f32_16x16x32_bf16 v[2:5], v[190:193], v[240:243], v[2:5]
	v_mfma_f32_16x16x32_bf16 v[56:59], v[186:189], v[202:205], v[56:59]
	v_mfma_f32_16x16x32_bf16 v[52:55], v[194:197], v[202:205], v[52:55]
	v_mfma_f32_16x16x32_bf16 v[40:43], v[186:189], v[228:231], v[40:43]
	v_mfma_f32_16x16x32_bf16 v[36:39], v[194:197], v[228:231], v[36:39]
	s_setprio 2
	s_barrier
	v_mfma_f32_16x16x32_bf16 v[24:27], v[186:189], v[236:239], v[24:27]
	v_mfma_f32_16x16x32_bf16 v[20:23], v[194:197], v[236:239], v[20:23]
	v_mfma_f32_16x16x32_bf16 v[6:9], v[186:189], v[244:247], v[6:9]
	v_mfma_f32_16x16x32_bf16 v[2:5], v[194:197], v[244:247], v[2:5]
	s_setprio 0
	s_add_i32 s6, 0, 0x18000
	s_add_i32 s7, 0, 0x1c000
	v_add_u32_e32 v178, s6, v10
	v_add_u32_e32 v194, s7, v10
	ds_read_b128 v[166:169], v178
	ds_read_b128 v[170:173], v178 offset:1024
	ds_read_b128 v[174:177], v178 offset:2048
	ds_read_b128 v[178:181], v178 offset:3072
	ds_read_b128 v[182:185], v194
	ds_read_b128 v[186:189], v194 offset:1024
	ds_read_b128 v[190:193], v194 offset:2048
	ds_read_b128 v[194:197], v194 offset:3072
	s_add_u32 s2, s40, 0x80000
	s_addc_u32 s3, s41, 0
	s_mov_b32 m0, s50
	v_lshl_add_u64 v[220:221], s[2:3], 0, v[132:133]
	ds_read_b128 v[198:201], v161 offset:32768
	ds_read_b128 v[202:205], v161 offset:33792
	ds_read_b128 v[212:215], v161 offset:34816
	ds_read_b128 v[228:231], v161 offset:35840
	ds_read_b128 v[232:235], v161 offset:36864
	ds_read_b128 v[236:239], v161 offset:37888
	ds_read_b128 v[240:243], v161 offset:38912
	ds_read_b128 v[244:247], v161 offset:39936
	global_load_lds_dwordx4 v[220:221], off
	v_lshl_add_u64 v[220:221], s[2:3], 0, v[136:137]
	s_mov_b32 m0, s51
	s_nop 0
	global_load_lds_dwordx4 v[220:221], off
	s_waitcnt vmcnt(8)
	s_waitcnt lgkmcnt(0)
	s_barrier
	s_setprio 1
	s_waitcnt lgkmcnt(0)
	v_mfma_f32_16x16x32_bf16 v[128:131], v[166:169], v[198:201], v[128:131]
	v_mfma_f32_16x16x32_bf16 v[124:127], v[174:177], v[198:201], v[124:127]
	v_mfma_f32_16x16x32_bf16 v[112:115], v[166:169], v[212:215], v[112:115]
	v_mfma_f32_16x16x32_bf16 v[108:111], v[174:177], v[212:215], v[108:111]
	v_mfma_f32_16x16x32_bf16 v[96:99], v[166:169], v[232:235], v[96:99]
	v_mfma_f32_16x16x32_bf16 v[92:95], v[174:177], v[232:235], v[92:95]
	v_mfma_f32_16x16x32_bf16 v[80:83], v[166:169], v[240:243], v[80:83]
	v_mfma_f32_16x16x32_bf16 v[76:79], v[174:177], v[240:243], v[76:79]
	v_mfma_f32_16x16x32_bf16 v[128:131], v[170:173], v[202:205], v[128:131]
	v_mfma_f32_16x16x32_bf16 v[124:127], v[178:181], v[202:205], v[124:127]
	v_mfma_f32_16x16x32_bf16 v[112:115], v[170:173], v[228:231], v[112:115]
	v_mfma_f32_16x16x32_bf16 v[108:111], v[178:181], v[228:231], v[108:111]
	v_mfma_f32_16x16x32_bf16 v[96:99], v[170:173], v[236:239], v[96:99]
	v_mfma_f32_16x16x32_bf16 v[92:95], v[178:181], v[236:239], v[92:95]
	v_mfma_f32_16x16x32_bf16 v[80:83], v[170:173], v[244:247], v[80:83]
	v_mfma_f32_16x16x32_bf16 v[76:79], v[178:181], v[244:247], v[76:79]
	s_setprio 0
	s_setprio 1
	v_mfma_f32_16x16x32_bf16 v[120:123], v[182:185], v[198:201], v[120:123]
	v_mfma_f32_16x16x32_bf16 v[116:119], v[190:193], v[198:201], v[116:119]
	v_mfma_f32_16x16x32_bf16 v[104:107], v[182:185], v[212:215], v[104:107]
	v_mfma_f32_16x16x32_bf16 v[100:103], v[190:193], v[212:215], v[100:103]
	v_mfma_f32_16x16x32_bf16 v[88:91], v[182:185], v[232:235], v[88:91]
	v_mfma_f32_16x16x32_bf16 v[84:87], v[190:193], v[232:235], v[84:87]
	v_mfma_f32_16x16x32_bf16 v[72:75], v[182:185], v[240:243], v[72:75]
	v_mfma_f32_16x16x32_bf16 v[68:71], v[190:193], v[240:243], v[68:71]
	v_mfma_f32_16x16x32_bf16 v[120:123], v[186:189], v[202:205], v[120:123]
	v_mfma_f32_16x16x32_bf16 v[116:119], v[194:197], v[202:205], v[116:119]
	v_mfma_f32_16x16x32_bf16 v[104:107], v[186:189], v[228:231], v[104:107]
	v_mfma_f32_16x16x32_bf16 v[100:103], v[194:197], v[228:231], v[100:103]
	s_setprio 2
	s_barrier
	v_mfma_f32_16x16x32_bf16 v[88:91], v[186:189], v[236:239], v[88:91]
	v_mfma_f32_16x16x32_bf16 v[84:87], v[194:197], v[236:239], v[84:87]
	v_mfma_f32_16x16x32_bf16 v[72:75], v[186:189], v[244:247], v[72:75]
	v_mfma_f32_16x16x32_bf16 v[68:71], v[194:197], v[244:247], v[68:71]
	s_setprio 0
	s_add_i32 s2, s6, s47
	v_lshl_add_u64 v[148:149], v[148:149], 0, s[86:87]
	s_mov_b32 m0, s2
	ds_read_b128 v[198:201], v161 offset:49152
	ds_read_b128 v[202:205], v161 offset:50176
	ds_read_b128 v[212:215], v161 offset:51200
	ds_read_b128 v[228:231], v161 offset:52224
	ds_read_b128 v[232:235], v161 offset:53248
	ds_read_b128 v[236:239], v161 offset:54272
	ds_read_b128 v[240:243], v161 offset:55296
	ds_read_b128 v[244:247], v161 offset:56320
	global_load_lds_dwordx4 v[148:149], off
	s_add_i32 m0, s2, 0x2000
	s_add_u32 s2, s34, 0x80080
	v_lshl_add_u64 v[148:149], v[216:217], 0, s[86:87]
	s_addc_u32 s3, s35, 0
	s_add_i32 s6, s7, s47
	global_load_lds_dwordx4 v[148:149], off
	v_lshl_add_u64 v[148:149], s[2:3], 0, v[134:135]
	s_mov_b32 m0, s6
	s_nop 0
	global_load_lds_dwordx4 v[148:149], off
	v_lshl_add_u64 v[148:149], s[2:3], 0, v[138:139]
	s_add_i32 m0, s6, 0x2000
	s_nop 0
	global_load_lds_dwordx4 v[148:149], off
	v_lshl_add_u64 v[148:149], v[218:219], 0, s[86:87]
	s_mov_b32 m0, s53
	s_nop 0
	global_load_lds_dwordx4 v[148:149], off
	v_lshl_add_u64 v[148:149], v[248:249], 0, s[86:87]
	s_mov_b32 m0, s54
	s_nop 0
	global_load_lds_dwordx4 v[148:149], off
	s_waitcnt vmcnt(8)
	s_waitcnt lgkmcnt(0)
	s_barrier
	s_setprio 1
	s_waitcnt lgkmcnt(0)
	v_mfma_f32_16x16x32_bf16 v[64:67], v[166:169], v[198:201], v[64:67]
	v_mfma_f32_16x16x32_bf16 v[60:63], v[174:177], v[198:201], v[60:63]
	v_mfma_f32_16x16x32_bf16 v[48:51], v[166:169], v[212:215], v[48:51]
	v_mfma_f32_16x16x32_bf16 v[44:47], v[174:177], v[212:215], v[44:47]
	v_mfma_f32_16x16x32_bf16 v[32:35], v[166:169], v[232:235], v[32:35]
	v_mfma_f32_16x16x32_bf16 v[28:31], v[174:177], v[232:235], v[28:31]
	v_mfma_f32_16x16x32_bf16 v[16:19], v[166:169], v[240:243], v[16:19]
	v_mfma_f32_16x16x32_bf16 v[12:15], v[174:177], v[240:243], v[12:15]
	v_mfma_f32_16x16x32_bf16 v[64:67], v[170:173], v[202:205], v[64:67]
	v_mfma_f32_16x16x32_bf16 v[60:63], v[178:181], v[202:205], v[60:63]
	v_mfma_f32_16x16x32_bf16 v[48:51], v[170:173], v[228:231], v[48:51]
	v_mfma_f32_16x16x32_bf16 v[44:47], v[178:181], v[228:231], v[44:47]
	v_mfma_f32_16x16x32_bf16 v[32:35], v[170:173], v[236:239], v[32:35]
	v_mfma_f32_16x16x32_bf16 v[28:31], v[178:181], v[236:239], v[28:31]
	v_mfma_f32_16x16x32_bf16 v[16:19], v[170:173], v[244:247], v[16:19]
	v_mfma_f32_16x16x32_bf16 v[12:15], v[178:181], v[244:247], v[12:15]
	s_setprio 0
	s_setprio 1
	v_mfma_f32_16x16x32_bf16 v[56:59], v[182:185], v[198:201], v[56:59]
	v_mfma_f32_16x16x32_bf16 v[52:55], v[190:193], v[198:201], v[52:55]
	v_mfma_f32_16x16x32_bf16 v[40:43], v[182:185], v[212:215], v[40:43]
	v_mfma_f32_16x16x32_bf16 v[36:39], v[190:193], v[212:215], v[36:39]
	v_mfma_f32_16x16x32_bf16 v[24:27], v[182:185], v[232:235], v[24:27]
	v_mfma_f32_16x16x32_bf16 v[20:23], v[190:193], v[232:235], v[20:23]
	v_mfma_f32_16x16x32_bf16 v[6:9], v[182:185], v[240:243], v[6:9]
	v_mfma_f32_16x16x32_bf16 v[2:5], v[190:193], v[240:243], v[2:5]
	v_mfma_f32_16x16x32_bf16 v[56:59], v[186:189], v[202:205], v[56:59]
	v_mfma_f32_16x16x32_bf16 v[52:55], v[194:197], v[202:205], v[52:55]
	v_mfma_f32_16x16x32_bf16 v[40:43], v[186:189], v[228:231], v[40:43]
	v_mfma_f32_16x16x32_bf16 v[36:39], v[194:197], v[228:231], v[36:39]
	s_setprio 2
	s_barrier
	v_mfma_f32_16x16x32_bf16 v[24:27], v[186:189], v[236:239], v[24:27]
	v_mfma_f32_16x16x32_bf16 v[20:23], v[194:197], v[236:239], v[20:23]
	v_mfma_f32_16x16x32_bf16 v[6:9], v[186:189], v[244:247], v[6:9]
	v_mfma_f32_16x16x32_bf16 v[2:5], v[194:197], v[244:247], v[2:5]
	s_setprio 0
	s_add_i32 s61, s61, 2
	s_add_u32 s30, s30, 0x100
	s_addc_u32 s31, s31, 0
	s_add_u32 s59, s59, 0x100
	s_addc_u32 s60, s60, 0
	s_cmp_gt_u32 s61, 29
	s_cbranch_scc0 .LBB0_1077
	s_and_b64 vcc, exec, s[4:5]
	s_cbranch_vccz .LBB0_1080
	s_barrier

.LBB0_2857:
	s_add_i32 s58, s2, 2
	s_add_u32 s3, s0, 0x80
	s_addc_u32 s4, s1, 0
	s_add_i32 s6, 0, 0x10000
	s_cmp_eq_u32 s55, s2
	s_cselect_b32 s5, s8, s4
	s_cselect_b32 s4, s9, s3
	v_add_u32_e32 v148, s6, v10
	s_cselect_b32 s3, s33, s49
	s_cselect_b32 s2, s41, s47
	s_add_i32 s7, 0, 0x14000
	ds_read_b128 v[144:147], v148
	ds_read_b128 v[166:169], v148 offset:1024
	ds_read_b128 v[170:173], v148 offset:2048
	ds_read_b128 v[174:177], v148 offset:3072
	v_add_u32_e32 v148, s7, v10
	ds_read_b128 v[178:181], v148
	ds_read_b128 v[182:185], v148 offset:1024
	ds_read_b128 v[186:189], v148 offset:2048
	ds_read_b128 v[190:193], v148 offset:3072
	v_lshl_add_u64 v[148:149], s[0:1], 0, v[140:141]
	s_add_i32 m0, s28, 0xc000
	ds_read_b128 v[194:197], v161
	ds_read_b128 v[198:201], v161 offset:1024
	ds_read_b128 v[202:205], v161 offset:2048
	ds_read_b128 v[212:215], v161 offset:3072
	ds_read_b128 v[228:231], v161 offset:4096
	ds_read_b128 v[232:235], v161 offset:5120
	ds_read_b128 v[236:239], v161 offset:6144
	ds_read_b128 v[240:243], v161 offset:7168
	global_load_lds_dwordx4 v[148:149], off
	v_lshl_add_u64 v[148:149], s[0:1], 0, v[142:143]
	s_add_i32 m0, s28, 0xe000
	s_nop 0
	global_load_lds_dwordx4 v[148:149], off
	s_waitcnt vmcnt(8)
	s_waitcnt lgkmcnt(0)
	s_barrier
	s_setprio 1
	s_waitcnt lgkmcnt(0)
	v_mfma_f32_16x16x32_bf16 v[128:131], v[144:147], v[194:197], v[128:131]
	v_mfma_f32_16x16x32_bf16 v[124:127], v[170:173], v[194:197], v[124:127]
	v_mfma_f32_16x16x32_bf16 v[112:115], v[144:147], v[202:205], v[112:115]
	v_mfma_f32_16x16x32_bf16 v[108:111], v[170:173], v[202:205], v[108:111]
	v_mfma_f32_16x16x32_bf16 v[96:99], v[144:147], v[228:231], v[96:99]
	v_mfma_f32_16x16x32_bf16 v[92:95], v[170:173], v[228:231], v[92:95]
	v_mfma_f32_16x16x32_bf16 v[80:83], v[144:147], v[236:239], v[80:83]
	v_mfma_f32_16x16x32_bf16 v[76:79], v[170:173], v[236:239], v[76:79]
	v_mfma_f32_16x16x32_bf16 v[128:131], v[166:169], v[198:201], v[128:131]
	v_mfma_f32_16x16x32_bf16 v[124:127], v[174:177], v[198:201], v[124:127]
	v_mfma_f32_16x16x32_bf16 v[112:115], v[166:169], v[212:215], v[112:115]
	v_mfma_f32_16x16x32_bf16 v[108:111], v[174:177], v[212:215], v[108:111]
	v_mfma_f32_16x16x32_bf16 v[96:99], v[166:169], v[232:235], v[96:99]
	v_mfma_f32_16x16x32_bf16 v[92:95], v[174:177], v[232:235], v[92:95]
	v_mfma_f32_16x16x32_bf16 v[80:83], v[166:169], v[240:243], v[80:83]
	v_mfma_f32_16x16x32_bf16 v[76:79], v[174:177], v[240:243], v[76:79]
	s_setprio 0
	s_setprio 1
	v_mfma_f32_16x16x32_bf16 v[120:123], v[178:181], v[194:197], v[120:123]
	v_mfma_f32_16x16x32_bf16 v[116:119], v[186:189], v[194:197], v[116:119]
	v_mfma_f32_16x16x32_bf16 v[104:107], v[178:181], v[202:205], v[104:107]
	v_mfma_f32_16x16x32_bf16 v[100:103], v[186:189], v[202:205], v[100:103]
	v_mfma_f32_16x16x32_bf16 v[88:91], v[178:181], v[228:231], v[88:91]
	v_mfma_f32_16x16x32_bf16 v[84:87], v[186:189], v[228:231], v[84:87]
	v_mfma_f32_16x16x32_bf16 v[72:75], v[178:181], v[236:239], v[72:75]
	v_mfma_f32_16x16x32_bf16 v[68:71], v[186:189], v[236:239], v[68:71]
	v_mfma_f32_16x16x32_bf16 v[120:123], v[182:185], v[198:201], v[120:123]
	v_mfma_f32_16x16x32_bf16 v[116:119], v[190:193], v[198:201], v[116:119]
	v_mfma_f32_16x16x32_bf16 v[104:107], v[182:185], v[212:215], v[104:107]
	v_mfma_f32_16x16x32_bf16 v[100:103], v[190:193], v[212:215], v[100:103]
	s_setprio 2
	s_barrier
	v_mfma_f32_16x16x32_bf16 v[88:91], v[182:185], v[232:235], v[88:91]
	v_mfma_f32_16x16x32_bf16 v[84:87], v[190:193], v[232:235], v[84:87]
	v_mfma_f32_16x16x32_bf16 v[72:75], v[182:185], v[240:243], v[72:75]
	v_mfma_f32_16x16x32_bf16 v[68:71], v[190:193], v[240:243], v[68:71]
	s_setprio 0
	s_add_i32 s6, s6, s22
	v_lshl_add_u64 v[148:149], s[2:3], 0, v[136:137]
	s_mov_b32 m0, s6
	ds_read_b128 v[194:197], v161 offset:16384
	ds_read_b128 v[198:201], v161 offset:17408
	ds_read_b128 v[202:205], v161 offset:18432
	ds_read_b128 v[212:215], v161 offset:19456
	ds_read_b128 v[228:231], v161 offset:20480
	ds_read_b128 v[232:235], v161 offset:21504
	ds_read_b128 v[236:239], v161 offset:22528
	ds_read_b128 v[240:243], v161 offset:23552
	global_load_lds_dwordx4 v[148:149], off
	s_add_i32 m0, s6, 0x2000
	v_lshl_add_u64 v[216:217], s[2:3], 0, v[132:133]
	s_add_u32 s2, s2, s40
	s_addc_u32 s3, s3, 0
	s_add_i32 s6, s7, s22
	global_load_lds_dwordx4 v[216:217], off
	v_lshl_add_u64 v[218:219], s[2:3], 0, v[136:137]
	s_mov_b32 m0, s6
	v_lshl_add_u64 v[220:221], s[2:3], 0, v[132:133]
	global_load_lds_dwordx4 v[218:219], off
	s_add_i32 m0, s6, 0x2000
	v_lshl_add_u64 v[244:245], s[4:5], 0, v[138:139]
	global_load_lds_dwordx4 v[220:221], off
	s_mov_b32 m0, s28
	v_lshl_add_u64 v[246:247], s[4:5], 0, v[134:135]
	global_load_lds_dwordx4 v[244:245], off
	s_mov_b32 m0, s29
	s_nop 0
	global_load_lds_dwordx4 v[246:247], off
	s_waitcnt vmcnt(8)
	s_waitcnt lgkmcnt(0)
	s_barrier
	s_setprio 1
	s_waitcnt lgkmcnt(0)
	v_mfma_f32_16x16x32_bf16 v[64:67], v[144:147], v[194:197], v[64:67]
	v_mfma_f32_16x16x32_bf16 v[60:63], v[170:173], v[194:197], v[60:63]
	v_mfma_f32_16x16x32_bf16 v[48:51], v[144:147], v[202:205], v[48:51]
	v_mfma_f32_16x16x32_bf16 v[44:47], v[170:173], v[202:205], v[44:47]
	v_mfma_f32_16x16x32_bf16 v[32:35], v[144:147], v[228:231], v[32:35]
	v_mfma_f32_16x16x32_bf16 v[28:31], v[170:173], v[228:231], v[28:31]
	v_mfma_f32_16x16x32_bf16 v[16:19], v[144:147], v[236:239], v[16:19]
	v_mfma_f32_16x16x32_bf16 v[12:15], v[170:173], v[236:239], v[12:15]
	v_mfma_f32_16x16x32_bf16 v[64:67], v[166:169], v[198:201], v[64:67]
	v_mfma_f32_16x16x32_bf16 v[60:63], v[174:177], v[198:201], v[60:63]
	v_mfma_f32_16x16x32_bf16 v[48:51], v[166:169], v[212:215], v[48:51]
	v_mfma_f32_16x16x32_bf16 v[44:47], v[174:177], v[212:215], v[44:47]
	v_mfma_f32_16x16x32_bf16 v[32:35], v[166:169], v[232:235], v[32:35]
	v_mfma_f32_16x16x32_bf16 v[28:31], v[174:177], v[232:235], v[28:31]
	v_mfma_f32_16x16x32_bf16 v[16:19], v[166:169], v[240:243], v[16:19]
	v_mfma_f32_16x16x32_bf16 v[12:15], v[174:177], v[240:243], v[12:15]
	s_setprio 0
	s_setprio 1
	v_mfma_f32_16x16x32_bf16 v[56:59], v[178:181], v[194:197], v[56:59]
	v_mfma_f32_16x16x32_bf16 v[52:55], v[186:189], v[194:197], v[52:55]
	v_mfma_f32_16x16x32_bf16 v[40:43], v[178:181], v[202:205], v[40:43]
	v_mfma_f32_16x16x32_bf16 v[36:39], v[186:189], v[202:205], v[36:39]
	v_mfma_f32_16x16x32_bf16 v[24:27], v[178:181], v[228:231], v[24:27]
	v_mfma_f32_16x16x32_bf16 v[20:23], v[186:189], v[228:231], v[20:23]
	v_mfma_f32_16x16x32_bf16 v[6:9], v[178:181], v[236:239], v[6:9]
	v_mfma_f32_16x16x32_bf16 v[2:5], v[186:189], v[236:239], v[2:5]
	v_mfma_f32_16x16x32_bf16 v[56:59], v[182:185], v[198:201], v[56:59]
	v_mfma_f32_16x16x32_bf16 v[52:55], v[190:193], v[198:201], v[52:55]
	v_mfma_f32_16x16x32_bf16 v[40:43], v[182:185], v[212:215], v[40:43]
	v_mfma_f32_16x16x32_bf16 v[36:39], v[190:193], v[212:215], v[36:39]
	s_setprio 2
	s_barrier
	v_mfma_f32_16x16x32_bf16 v[24:27], v[182:185], v[232:235], v[24:27]
	v_mfma_f32_16x16x32_bf16 v[20:23], v[190:193], v[232:235], v[20:23]
	v_mfma_f32_16x16x32_bf16 v[6:9], v[182:185], v[240:243], v[6:9]
	v_mfma_f32_16x16x32_bf16 v[2:5], v[190:193], v[240:243], v[2:5]
	s_setprio 0
	s_add_i32 s6, 0, 0x18000
	s_add_i32 s7, 0, 0x1c000
	v_add_u32_e32 v174, s6, v10
	v_add_u32_e32 v190, s7, v10
	ds_read_b128 v[144:147], v174
	ds_read_b128 v[166:169], v174 offset:1024
	ds_read_b128 v[170:173], v174 offset:2048
	ds_read_b128 v[174:177], v174 offset:3072
	ds_read_b128 v[178:181], v190
	ds_read_b128 v[182:185], v190 offset:1024
	ds_read_b128 v[186:189], v190 offset:2048
	ds_read_b128 v[190:193], v190 offset:3072
	s_add_u32 s2, s4, s40
	s_addc_u32 s3, s5, 0
	s_mov_b32 m0, s30
	v_lshl_add_u64 v[248:249], s[2:3], 0, v[138:139]
	ds_read_b128 v[194:197], v161 offset:32768
	ds_read_b128 v[198:201], v161 offset:33792
	ds_read_b128 v[202:205], v161 offset:34816
	ds_read_b128 v[212:215], v161 offset:35840
	ds_read_b128 v[228:231], v161 offset:36864
	ds_read_b128 v[232:235], v161 offset:37888
	ds_read_b128 v[236:239], v161 offset:38912
	ds_read_b128 v[240:243], v161 offset:39936
	global_load_lds_dwordx4 v[248:249], off
	v_lshl_add_u64 v[248:249], s[2:3], 0, v[134:135]
	s_mov_b32 m0, s31
	s_nop 0
	global_load_lds_dwordx4 v[248:249], off
	s_waitcnt vmcnt(8)
	s_waitcnt lgkmcnt(0)
	s_barrier
	s_setprio 1
	s_waitcnt lgkmcnt(0)
	v_mfma_f32_16x16x32_bf16 v[128:131], v[144:147], v[194:197], v[128:131]
	v_mfma_f32_16x16x32_bf16 v[124:127], v[170:173], v[194:197], v[124:127]
	v_mfma_f32_16x16x32_bf16 v[112:115], v[144:147], v[202:205], v[112:115]
	v_mfma_f32_16x16x32_bf16 v[108:111], v[170:173], v[202:205], v[108:111]
	v_mfma_f32_16x16x32_bf16 v[96:99], v[144:147], v[228:231], v[96:99]
	v_mfma_f32_16x16x32_bf16 v[92:95], v[170:173], v[228:231], v[92:95]
	v_mfma_f32_16x16x32_bf16 v[80:83], v[144:147], v[236:239], v[80:83]
	v_mfma_f32_16x16x32_bf16 v[76:79], v[170:173], v[236:239], v[76:79]
	v_mfma_f32_16x16x32_bf16 v[128:131], v[166:169], v[198:201], v[128:131]
	v_mfma_f32_16x16x32_bf16 v[124:127], v[174:177], v[198:201], v[124:127]
	v_mfma_f32_16x16x32_bf16 v[112:115], v[166:169], v[212:215], v[112:115]
	v_mfma_f32_16x16x32_bf16 v[108:111], v[174:177], v[212:215], v[108:111]
	v_mfma_f32_16x16x32_bf16 v[96:99], v[166:169], v[232:235], v[96:99]
	v_mfma_f32_16x16x32_bf16 v[92:95], v[174:177], v[232:235], v[92:95]
	v_mfma_f32_16x16x32_bf16 v[80:83], v[166:169], v[240:243], v[80:83]
	v_mfma_f32_16x16x32_bf16 v[76:79], v[174:177], v[240:243], v[76:79]
	s_setprio 0
	s_setprio 1
	v_mfma_f32_16x16x32_bf16 v[120:123], v[178:181], v[194:197], v[120:123]
	v_mfma_f32_16x16x32_bf16 v[116:119], v[186:189], v[194:197], v[116:119]
	v_mfma_f32_16x16x32_bf16 v[104:107], v[178:181], v[202:205], v[104:107]
	v_mfma_f32_16x16x32_bf16 v[100:103], v[186:189], v[202:205], v[100:103]
	v_mfma_f32_16x16x32_bf16 v[88:91], v[178:181], v[228:231], v[88:91]
	v_mfma_f32_16x16x32_bf16 v[84:87], v[186:189], v[228:231], v[84:87]
	v_mfma_f32_16x16x32_bf16 v[72:75], v[178:181], v[236:239], v[72:75]
	v_mfma_f32_16x16x32_bf16 v[68:71], v[186:189], v[236:239], v[68:71]
	v_mfma_f32_16x16x32_bf16 v[120:123], v[182:185], v[198:201], v[120:123]
	v_mfma_f32_16x16x32_bf16 v[116:119], v[190:193], v[198:201], v[116:119]
	v_mfma_f32_16x16x32_bf16 v[104:107], v[182:185], v[212:215], v[104:107]
	v_mfma_f32_16x16x32_bf16 v[100:103], v[190:193], v[212:215], v[100:103]
	s_setprio 2
	s_barrier
	v_mfma_f32_16x16x32_bf16 v[88:91], v[182:185], v[232:235], v[88:91]
	v_mfma_f32_16x16x32_bf16 v[84:87], v[190:193], v[232:235], v[84:87]
	v_mfma_f32_16x16x32_bf16 v[72:75], v[182:185], v[240:243], v[72:75]
	v_mfma_f32_16x16x32_bf16 v[68:71], v[190:193], v[240:243], v[68:71]
	s_setprio 0
	s_add_i32 s2, s6, s22
	v_lshl_add_u64 v[148:149], v[148:149], 0, s[86:87]
	s_mov_b32 m0, s2
	ds_read_b128 v[194:197], v161 offset:49152
	ds_read_b128 v[198:201], v161 offset:50176
	ds_read_b128 v[202:205], v161 offset:51200
	ds_read_b128 v[212:215], v161 offset:52224
	ds_read_b128 v[228:231], v161 offset:53248
	ds_read_b128 v[232:235], v161 offset:54272
	ds_read_b128 v[236:239], v161 offset:55296
	ds_read_b128 v[240:243], v161 offset:56320
	global_load_lds_dwordx4 v[148:149], off
	v_lshl_add_u64 v[148:149], v[216:217], 0, s[86:87]
	s_add_i32 m0, s2, 0x2000
	s_add_i32 s2, s7, s22
	global_load_lds_dwordx4 v[148:149], off
	v_lshl_add_u64 v[148:149], v[218:219], 0, s[86:87]
	s_mov_b32 m0, s2
	s_nop 0
	global_load_lds_dwordx4 v[148:149], off
	v_lshl_add_u64 v[148:149], v[220:221], 0, s[86:87]
	s_add_i32 m0, s2, 0x2000
	s_nop 0
	global_load_lds_dwordx4 v[148:149], off
	v_lshl_add_u64 v[148:149], v[244:245], 0, s[86:87]
	s_mov_b32 m0, s34
	s_nop 0
	global_load_lds_dwordx4 v[148:149], off
	v_lshl_add_u64 v[148:149], v[246:247], 0, s[86:87]
	s_mov_b32 m0, s35
	s_nop 0
	global_load_lds_dwordx4 v[148:149], off
	s_waitcnt vmcnt(8)
	s_waitcnt lgkmcnt(0)
	s_barrier
	s_setprio 1
	s_waitcnt lgkmcnt(0)
	v_mfma_f32_16x16x32_bf16 v[64:67], v[144:147], v[194:197], v[64:67]
	v_mfma_f32_16x16x32_bf16 v[60:63], v[170:173], v[194:197], v[60:63]
	v_mfma_f32_16x16x32_bf16 v[48:51], v[144:147], v[202:205], v[48:51]
	v_mfma_f32_16x16x32_bf16 v[44:47], v[170:173], v[202:205], v[44:47]
	v_mfma_f32_16x16x32_bf16 v[32:35], v[144:147], v[228:231], v[32:35]
	v_mfma_f32_16x16x32_bf16 v[28:31], v[170:173], v[228:231], v[28:31]
	v_mfma_f32_16x16x32_bf16 v[16:19], v[144:147], v[236:239], v[16:19]
	v_mfma_f32_16x16x32_bf16 v[12:15], v[170:173], v[236:239], v[12:15]
	v_mfma_f32_16x16x32_bf16 v[64:67], v[166:169], v[198:201], v[64:67]
	v_mfma_f32_16x16x32_bf16 v[60:63], v[174:177], v[198:201], v[60:63]
	v_mfma_f32_16x16x32_bf16 v[48:51], v[166:169], v[212:215], v[48:51]
	v_mfma_f32_16x16x32_bf16 v[44:47], v[174:177], v[212:215], v[44:47]
	v_mfma_f32_16x16x32_bf16 v[32:35], v[166:169], v[232:235], v[32:35]
	v_mfma_f32_16x16x32_bf16 v[28:31], v[174:177], v[232:235], v[28:31]
	v_mfma_f32_16x16x32_bf16 v[16:19], v[166:169], v[240:243], v[16:19]
	v_mfma_f32_16x16x32_bf16 v[12:15], v[174:177], v[240:243], v[12:15]
	s_setprio 0
	s_setprio 1
	v_mfma_f32_16x16x32_bf16 v[56:59], v[178:181], v[194:197], v[56:59]
	v_mfma_f32_16x16x32_bf16 v[52:55], v[186:189], v[194:197], v[52:55]
	v_mfma_f32_16x16x32_bf16 v[40:43], v[178:181], v[202:205], v[40:43]
	v_mfma_f32_16x16x32_bf16 v[36:39], v[186:189], v[202:205], v[36:39]
	v_mfma_f32_16x16x32_bf16 v[24:27], v[178:181], v[228:231], v[24:27]
	v_mfma_f32_16x16x32_bf16 v[20:23], v[186:189], v[228:231], v[20:23]
	v_mfma_f32_16x16x32_bf16 v[6:9], v[178:181], v[236:239], v[6:9]
	v_mfma_f32_16x16x32_bf16 v[2:5], v[186:189], v[236:239], v[2:5]
	v_mfma_f32_16x16x32_bf16 v[56:59], v[182:185], v[198:201], v[56:59]
	v_mfma_f32_16x16x32_bf16 v[52:55], v[190:193], v[198:201], v[52:55]
	v_mfma_f32_16x16x32_bf16 v[40:43], v[182:185], v[212:215], v[40:43]
	v_mfma_f32_16x16x32_bf16 v[36:39], v[190:193], v[212:215], v[36:39]
	s_setprio 2
	s_barrier
	v_mfma_f32_16x16x32_bf16 v[24:27], v[182:185], v[232:235], v[24:27]
	v_mfma_f32_16x16x32_bf16 v[20:23], v[190:193], v[232:235], v[20:23]
	v_mfma_f32_16x16x32_bf16 v[6:9], v[182:185], v[240:243], v[6:9]
	v_mfma_f32_16x16x32_bf16 v[2:5], v[190:193], v[240:243], v[2:5]
	s_setprio 0
	s_add_u32 s0, s0, 0x100
	s_addc_u32 s1, s1, 0
	s_add_u32 s47, s47, 0x100
	s_addc_u32 s49, s49, 0
	s_cmp_ge_u32 s58, s54
	s_mov_b32 s2, s58
	s_cbranch_scc0 .LBB0_2857
	s_and_b64 vcc, exec, s[44:45]
	s_cbranch_vccz .LBB0_2860
	s_barrier
